# scan A step loop (phase 4): counted vmcnt waits instead of vmcnt(0) drains, decay loads of the second unrolled step hoisted to its start
# speedup vs baseline: 1.0031x; 1.0031x over previous
; template <bool OUT>
; DI void scan_segment(const P& p, f32x16 (&S)[4], int b, int hd, int dir, int s0, int s1, float& dp0, float& dp1) {
;     ...
;   auto body = [&](int step, auto PP) {
;     constexpr int Q = decltype(PP)::value;
;     char* ib = img + Q * 32768;
; #pragma unroll
;     for (int e = 0; e < 2; ++e) { const int f = 2 * wid + e;
;       if (OUT) *(bf16x8*)(ib + f * 1024 + lane * 16) = kq[Q][e];
;       *(bf16x8*)(ib + (16 + f) * 1024 + lane * 16) = kk[Q][e]; }
;     const float c0 = d0[Q], c1 = d1[Q];
;     bool isctx; int n; size_t unit; scan_step_addr(p, b, hd, dir, step, isctx, n, unit);
;     __syncthreads();
;     fetch(min(step + 2, s1 - 1), PP, false);
.LBB0_302:
	s_add_i32 s31, s33, 2
	s_min_i32 s34, s31, s29
	s_cmp_gt_u32 s34, 3
	s_cselect_b64 s[18:19], -1, 0
	s_mov_b64 s[22:23], -1
	s_and_b64 vcc, exec, s[18:19]
	s_waitcnt vmcnt(8)
	ds_write_b128 v133, v[98:101] offset:16384
	ds_write_b128 v133, v[102:105] offset:17408
	s_waitcnt lgkmcnt(0)
	s_barrier
	s_cbranch_vccz .LBB0_304
	s_add_i32 s22, s34, -4
	s_sub_i32 s23, 0x103, s34
	s_and_b64 s[20:21], s[14:15], exec
	s_cselect_b32 s20, s22, s23
	s_add_i32 s20, s20, s28
	s_mov_b64 s[22:23], 0

; DI void scan_decay(f32x16 (&S)[4], float d0, float d1, int h2) {
; #pragma unroll
;   for (int a = 0; a < 4; ++a)
; #pragma unroll
;     for (int i = 0; i < 16; ++i) { const int src = 32 * (a & 1) + (i & 3) + 8 * (i >> 2) + 4 * h2; S[a][i] *= __shfl((a < 2) ? d0 : d1, src, 64); }
; }
; template <bool OUT>
; DI void scan_segment(const P& p, f32x16 (&S)[4], int b, int hd, int dir, int s0, int s1, float& dp0, float& dp1) {
;     ...
;     d0[Q] = dd[lane]; d1[Q] = dd[64 + lane];
;   };
;   auto fetch_v = [&](int step, auto PP) {
;     constexpr int Q = decltype(PP)::value;
;     bool isctx; int n; size_t unit; scan_step_addr(p, b, hd, dir, step, isctx, n, unit);
;     const bf16_t* vt = VT + unit * 16384 + (size_t)(wid * 32) * 64;
; #pragma unroll
;     for (int s = 0; s < 4; ++s) vb[Q][s] = *(const bf16x8*)(vt + r * 64 + s * 16 + h2 * 8);
;   };
;   auto body = [&](int step, auto PP) {
;     constexpr int Q = decltype(PP)::value;
;     char* ib = img + Q * 32768;
; #pragma unroll
;     for (int e = 0; e < 2; ++e) { const int f = 2 * wid + e;
;       if (OUT) *(bf16x8*)(ib + f * 1024 + lane * 16) = kq[Q][e];
;       *(bf16x8*)(ib + (16 + f) * 1024 + lane * 16) = kk[Q][e]; }
;     const float c0 = d0[Q], c1 = d1[Q];
;     bool isctx; int n; size_t unit; scan_step_addr(p, b, hd, dir, step, isctx, n, unit);
;     __syncthreads();
;     fetch(min(step + 2, s1 - 1), PP, false);
;     if (OUT && !isctx) {
;       f32x16 o0, o1;
; #pragma unroll
;       for (int i = 0; i < 16; ++i) { o0[i] = 0.f; o1[i] = 0.f; }
; #pragma unroll
;       for (int a = 0; a < 4; ++a)
; #pragma unroll
;         for (int s = 0; s < 2; ++s) { bf16x8 sb = pack8(S[a], s);
;           bf16x8 q0 = *(const bf16x8*)(ib + (a * 2 + s) * 1024 + lane * 16), q1 = *(const bf16x8*)(ib + (8 + a * 2 + s) * 1024 + lane * 16);
;           o0 = MFMA32(q0, sb, o0); o1 = MFMA32(q1, sb, o1); }
;       const int tl = otid(), ro = tl & 31, ho = (tl >> 5) & 1;
;       bf16_t* ob = OFB + (size_t)dir * T * 1024 + ((size_t)b * 16384 + (size_t)n * 64 + 4 * ho) * 1024 + hd * 256 + wid * 32 + ro;
; #pragma unroll
;       for (int i = 0; i < 16; ++i) { const int row = (i & 3) + 8 * (i >> 2); ob[(size_t)row * 1024] = f2bf(o0[i]); ob[(size_t)(32 + row) * 1024] = f2bf(o1[i]); }
;     }
;     if (!OUT || step + 1 < s1) {
;       scan_decay(S, c0, c1, h2);
;       if (!OUT && wid == 0) { dp0 *= c0; dp1 *= c1; }
; #pragma unroll
.LBB0_310:
	s_ashr_i32 s19, s18, 31
	s_lshl_b64 s[18:19], s[18:19], 17
	s_lshl_b64 s[20:21], s[20:21], 15
	v_lshl_add_u64 v[66:67], v[116:117], 0, s[18:19]
	v_lshl_add_u64 v[66:67], v[66:67], 0, s[20:21]
	v_mov_b32_e32 v129, v115
	v_lshl_add_u64 v[66:67], v[66:67], 0, v[128:129]
	global_load_dwordx4 v[78:81], v[66:67], off
	global_load_dwordx4 v[74:77], v[66:67], off offset:32
	global_load_dwordx4 v[70:73], v[66:67], off offset:64
	s_nop 0
	global_load_dwordx4 v[66:69], v[66:67], off offset:96
	v_mul_f32_e32 v170, v134, v170
	s_cmp_ge_u32 s33, s29
	v_mul_f32_e32 v169, v135, v169
	s_cbranch_scc1 .LBB0_316
	s_add_i32 s18, s33, 3
	s_min_i32 s22, s18, s29
	s_cmp_gt_u32 s22, 3
	s_cselect_b64 s[18:19], -1, 0
	s_cmp_lt_u32 s22, 4
	s_mov_b64 s[20:21], s[16:17]
	s_waitcnt vmcnt(8)
	ds_write_b128 v133, v[110:113] offset:49152
	ds_write_b128 v133, v[106:109] offset:50176
	s_waitcnt lgkmcnt(0)
	s_barrier
	s_cbranch_scc1 .LBB0_313
	s_add_i32 s23, s22, -4
	s_sub_i32 s33, 0x103, s22
	s_and_b64 s[20:21], s[14:15], exec
	s_cselect_b32 s20, s23, s33
	s_add_i32 s20, s20, s28
	s_ashr_i32 s21, s20, 31
	s_lshl_b64 s[20:21], s[20:21], 2
	s_or_b64 s[20:21], s[20:21], s[6:7]
.LBB0_313:
	s_lshl_b64 s[90:91], s[20:21], 1
	s_or_b64 s[90:91], s[90:91], s[10:11]
	s_lshl_b64 s[90:91], s[90:91], 9
	v_lshl_add_u64 v[192:193], v[118:119], 0, s[90:91]
	global_load_dword v190, v[192:193], off
	global_load_dword v191, v[192:193], off offset:256
	ds_bpermute_b32 v106, v132, v168
	ds_bpermute_b32 v107, v136, v168
	ds_bpermute_b32 v108, v137, v168
	ds_bpermute_b32 v109, v138, v168
	ds_bpermute_b32 v110, v139, v168
	ds_bpermute_b32 v111, v140, v168
	ds_bpermute_b32 v112, v141, v168
	ds_bpermute_b32 v113, v142, v168
	s_waitcnt lgkmcnt(4)
	v_pk_mul_f32 v[52:53], v[52:53], v[108:109]
	v_pk_mul_f32 v[50:51], v[50:51], v[106:107]
	s_waitcnt lgkmcnt(2)
	v_pk_mul_f32 v[54:55], v[54:55], v[110:111]
	ds_bpermute_b32 v106, v151, v168
	s_waitcnt lgkmcnt(1)
	v_pk_mul_f32 v[56:57], v[56:57], v[112:113]
	ds_bpermute_b32 v107, v152, v168
	ds_bpermute_b32 v108, v153, v168
	ds_bpermute_b32 v109, v154, v168
	ds_bpermute_b32 v110, v155, v168
	ds_bpermute_b32 v111, v156, v168
	ds_bpermute_b32 v112, v157, v168
	ds_bpermute_b32 v113, v158, v168
	s_waitcnt lgkmcnt(4)
	v_pk_mul_f32 v[36:37], v[36:37], v[108:109]
	v_pk_mul_f32 v[34:35], v[34:35], v[106:107]
	s_waitcnt lgkmcnt(2)
	v_pk_mul_f32 v[38:39], v[38:39], v[110:111]
	ds_bpermute_b32 v110, v132, v165
	s_waitcnt lgkmcnt(1)
	v_pk_mul_f32 v[40:41], v[40:41], v[112:113]
	ds_bpermute_b32 v111, v136, v165
	ds_bpermute_b32 v112, v137, v165
	ds_bpermute_b32 v113, v138, v165
	ds_bpermute_b32 v106, v139, v165
	ds_bpermute_b32 v107, v140, v165
	ds_bpermute_b32 v108, v141, v165
	ds_bpermute_b32 v109, v142, v165
	ds_bpermute_b32 v174, v143, v168
	ds_bpermute_b32 v176, v145, v168
	ds_bpermute_b32 v178, v147, v168
	ds_bpermute_b32 v180, v149, v168
	ds_bpermute_b32 v181, v150, v168
	ds_bpermute_b32 v179, v148, v168
	ds_bpermute_b32 v177, v146, v168
	ds_bpermute_b32 v175, v144, v168
	s_waitcnt lgkmcnt(8)
	v_pk_mul_f32 v[24:25], v[24:25], v[108:109]
	v_pk_mul_f32 v[22:23], v[22:23], v[106:107]
	ds_read_b128 v[106:109], v171 offset:49152
	v_pk_mul_f32 v[20:21], v[20:21], v[112:113]
	v_pk_mul_f32 v[18:19], v[18:19], v[110:111]
	ds_read_b128 v[110:113], v171 offset:50176
	s_waitcnt lgkmcnt(5)
	v_pk_mul_f32 v[64:65], v[64:65], v[180:181]
	s_waitcnt lgkmcnt(4)
	v_pk_mul_f32 v[62:63], v[62:63], v[178:179]
	s_waitcnt lgkmcnt(3)
	v_pk_mul_f32 v[60:61], v[60:61], v[176:177]
	s_waitcnt lgkmcnt(2)
	v_pk_mul_f32 v[58:59], v[58:59], v[174:175]
	ds_bpermute_b32 v174, v159, v168
	ds_bpermute_b32 v176, v161, v168
	ds_bpermute_b32 v178, v163, v168
	ds_bpermute_b32 v180, v166, v168
	ds_bpermute_b32 v181, v167, v168
	ds_bpermute_b32 v179, v164, v168
	ds_bpermute_b32 v177, v162, v168
	ds_bpermute_b32 v175, v160, v168
	s_waitcnt lgkmcnt(9)
	v_mfma_f32_32x32x16_bf16 v[50:65], v[106:109], v[94:97], v[50:65]
	s_waitcnt lgkmcnt(3)
	v_mul_f32_e64 v48, v48, v180
	v_mul_f32_e64 v49, v49, v181
	s_waitcnt lgkmcnt(2)
	v_mul_f32_e64 v46, v46, v178
	v_mul_f32_e64 v47, v47, v179
	s_waitcnt lgkmcnt(1)
	v_pk_mul_f32 v[44:45], v[44:45], v[176:177]
	s_waitcnt lgkmcnt(0)
; #define MFMA32(a, b, c) __builtin_amdgcn_mfma_f32_32x32x16_bf16((a), (b), (c), 0, 0, 0)
; template <bool OUT>
; DI void scan_segment(const P& p, f32x16 (&S)[4], int b, int hd, int dir, int s0, int s1, float& dp0, float& dp1) {
;     ...
;   auto fetch = [&](int step, auto PP, bool with_v) {
;     constexpr int Q = decltype(PP)::value;
;     bool isctx; int n; size_t unit; scan_step_addr(p, b, hd, dir, step, isctx, n, unit);
;     const bf16_t* qi = QI + (unit * 2 + dir) * 8192; const bf16_t* kst = KST + (unit * 2 + dir) * 8192; const float* dd = DD + (unit * 2 + dir) * 128;
;     const bf16_t* vt = VT + unit * 16384 + (size_t)(wid * 32) * 64;
; #pragma unroll
;     for (int e = 0; e < 2; ++e) { const int f = 2 * wid + e;
;       if (OUT) { const int m = f >> 3, a = (f >> 1) & 3, s = f & 1; kq[Q][e] = *(const bf16x8*)(qi + (32 * m + r) * 128 + a * 32 + s * 16 + h2 * 8); }
;       { const int s = f >> 2, a = f & 3; kk[Q][e] = *(const bf16x8*)(kst + (32 * a + r) * 64 + s * 16 + h2 * 8); } }
;     if (with_v) {
; #pragma unroll
;       for (int s = 0; s < 4; ++s) vb[Q][s] = *(const bf16x8*)(vt + r * 64 + s * 16 + h2 * 8); }
;     d0[Q] = dd[lane]; d1[Q] = dd[64 + lane];
;   };
;     ...
;     if (!OUT || step + 1 < s1) {
;       scan_decay(S, c0, c1, h2);
;       if (!OUT && wid == 0) { dp0 *= c0; dp1 *= c1; }
; #pragma unroll
;       for (int s = 0; s < 4; ++s)
; #pragma unroll
;         for (int a = 0; a < 4; ++a) { bf16x8 ka = *(const bf16x8*)(ib + (16 + s * 4 + a) * 1024 + lane * 16); S[a] = MFMA32(ka, vb[Q][s], S[a]); }
;     }
;     fetch_v(min(step + 2, s1 - 1), PP);
	v_pk_mul_f32 v[42:43], v[42:43], v[174:175]
	ds_bpermute_b32 v174, v143, v165
	ds_bpermute_b32 v176, v145, v165
	ds_bpermute_b32 v178, v147, v165
	ds_bpermute_b32 v180, v149, v165
	ds_bpermute_b32 v181, v150, v165
	ds_bpermute_b32 v179, v148, v165
	ds_bpermute_b32 v177, v146, v165
	ds_bpermute_b32 v175, v144, v165
	ds_read_b128 v[106:109], v171 offset:51200
	v_mfma_f32_32x32x16_bf16 v[34:49], v[110:113], v[94:97], v[34:49]
	ds_read_b128 v[110:113], v171 offset:52224
	s_waitcnt lgkmcnt(5)
	v_mul_f32_e64 v32, v32, v180
	v_mul_f32_e64 v33, v33, v181
	s_waitcnt lgkmcnt(4)
	v_pk_mul_f32 v[30:31], v[30:31], v[178:179]
	s_waitcnt lgkmcnt(3)
	v_pk_mul_f32 v[28:29], v[28:29], v[176:177]
	s_waitcnt lgkmcnt(2)
	v_pk_mul_f32 v[26:27], v[26:27], v[174:175]
	ds_bpermute_b32 v174, v151, v165
	ds_bpermute_b32 v175, v152, v165
	ds_bpermute_b32 v176, v153, v165
	ds_bpermute_b32 v177, v154, v165
	ds_bpermute_b32 v178, v155, v165
	ds_bpermute_b32 v179, v156, v165
	ds_bpermute_b32 v180, v157, v165
	ds_bpermute_b32 v181, v158, v165
	ds_bpermute_b32 v182, v159, v165
	ds_bpermute_b32 v183, v160, v165
	ds_bpermute_b32 v184, v166, v165
	ds_bpermute_b32 v185, v167, v165
	ds_bpermute_b32 v186, v161, v165
	ds_bpermute_b32 v188, v163, v165
	ds_bpermute_b32 v189, v164, v165
	ds_bpermute_b32 v187, v162, v165
	s_waitcnt lgkmcnt(4)
	v_pk_mul_f32 v[16:17], v[16:17], v[184:185]
	v_pk_mul_f32 v[10:11], v[10:11], v[182:183]
	v_pk_mul_f32 v[8:9], v[8:9], v[180:181]
	s_waitcnt lgkmcnt(1)
	v_pk_mul_f32 v[14:15], v[14:15], v[188:189]
	s_waitcnt lgkmcnt(0)
	v_pk_mul_f32 v[12:13], v[12:13], v[186:187]
	v_pk_mul_f32 v[6:7], v[6:7], v[178:179]
	v_pk_mul_f32 v[4:5], v[4:5], v[176:177]
	v_pk_mul_f32 v[2:3], v[2:3], v[174:175]
	v_mfma_f32_32x32x16_bf16 v[18:33], v[106:109], v[94:97], v[18:33]
	s_lshl_b64 s[20:21], s[20:21], 1
	s_or_b64 s[20:21], s[20:21], s[10:11]
	s_lshl_b64 s[34:35], s[20:21], 14
	s_add_u32 s34, s24, s34
	s_addc_u32 s35, s25, s35
	v_mov_b32_e32 v127, v115
	v_mov_b32_e32 v131, v115
	v_mfma_f32_32x32x16_bf16 v[2:17], v[110:113], v[94:97], v[2:17]
	ds_read_b128 v[94:97], v171 offset:53248
	ds_read_b128 v[106:109], v171 offset:54272
	v_mov_b32_e32 v129, v115
	s_lshl_b64 s[20:21], s[20:21], 9
	s_andn2_b64 vcc, exec, s[18:19]
	s_mov_b64 s[18:19], s[16:17]
	s_waitcnt lgkmcnt(1)
	v_mfma_f32_32x32x16_bf16 v[50:65], v[94:97], v[90:93], v[50:65]
	s_waitcnt lgkmcnt(0)
	v_mfma_f32_32x32x16_bf16 v[34:49], v[106:109], v[90:93], v[34:49]
	ds_read_b128 v[94:97], v171 offset:55296
	ds_read_b128 v[106:109], v171 offset:56320
	s_waitcnt lgkmcnt(1)
	v_mfma_f32_32x32x16_bf16 v[18:33], v[94:97], v[90:93], v[18:33]
	s_waitcnt lgkmcnt(0)
	v_mfma_f32_32x32x16_bf16 v[2:17], v[106:109], v[90:93], v[2:17]
	ds_read_b128 v[90:93], v171 offset:57344
	ds_read_b128 v[94:97], v171 offset:58368
	s_waitcnt lgkmcnt(1)
	v_mfma_f32_32x32x16_bf16 v[50:65], v[90:93], v[86:89], v[50:65]
	s_waitcnt lgkmcnt(0)
	v_mfma_f32_32x32x16_bf16 v[34:49], v[94:97], v[86:89], v[34:49]
	ds_read_b128 v[90:93], v171 offset:59392
	ds_read_b128 v[94:97], v171 offset:60416
	s_waitcnt lgkmcnt(1)
	v_mfma_f32_32x32x16_bf16 v[18:33], v[90:93], v[86:89], v[18:33]
	ds_read_b128 v[90:93], v171 offset:61440
	s_waitcnt lgkmcnt(1)
	v_mfma_f32_32x32x16_bf16 v[2:17], v[94:97], v[86:89], v[2:17]
	ds_read_b128 v[86:89], v171 offset:62464
	v_lshl_add_u64 v[94:95], s[34:35], 0, v[114:115]
	v_lshl_add_u64 v[96:97], s[34:35], 0, v[130:131]
	s_waitcnt lgkmcnt(1)
	v_mfma_f32_32x32x16_bf16 v[50:65], v[90:93], v[82:85], v[50:65]
	v_lshl_add_u64 v[90:91], v[94:95], 0, v[126:127]
	v_lshl_add_u64 v[94:95], v[90:91], 0, v[128:129]
	ds_read_b128 v[90:93], v171 offset:63488
	s_waitcnt lgkmcnt(1)
	v_mfma_f32_32x32x16_bf16 v[34:49], v[86:89], v[82:85], v[34:49]
	v_lshl_add_u64 v[86:87], v[96:97], 0, v[126:127]
	v_lshl_add_u64 v[86:87], v[86:87], 0, v[128:129]
	global_load_dwordx4 v[110:113], v[94:95], off
	global_load_dwordx4 v[106:109], v[86:87], off
	ds_read_b128 v[86:89], v171 offset:64512
	s_waitcnt lgkmcnt(1)
	v_mfma_f32_32x32x16_bf16 v[18:33], v[90:93], v[82:85], v[18:33]
	s_waitcnt lgkmcnt(0)
	v_mfma_f32_32x32x16_bf16 v[2:17], v[86:89], v[82:85], v[2:17]
	s_cbranch_vccnz .LBB0_315
	s_add_i32 s20, s22, -4
	s_sub_i32 s21, 0x103, s22
	s_and_b64 s[18:19], s[14:15], exec
	s_cselect_b32 s18, s20, s21
	s_add_i32 s18, s18, s28
	s_ashr_i32 s19, s18, 31
	s_lshl_b64 s[18:19], s[18:19], 2
	s_or_b64 s[18:19], s[18:19], s[6:7]

; #define MFMA32(a, b, c) __builtin_amdgcn_mfma_f32_32x32x16_bf16((a), (b), (c), 0, 0, 0)
; template <bool OUT>
; DI void scan_segment(const P& p, f32x16 (&S)[4], int b, int hd, int dir, int s0, int s1, float& dp0, float& dp1) {
;     ...
;     if (!OUT || step + 1 < s1) {
;       scan_decay(S, c0, c1, h2);
;       if (!OUT && wid == 0) { dp0 *= c0; dp1 *= c1; }
; #pragma unroll
;       for (int s = 0; s < 4; ++s)
; #pragma unroll
;         for (int a = 0; a < 4; ++a) { bf16x8 ka = *(const bf16x8*)(ib + (16 + s * 4 + a) * 1024 + lane * 16); S[a] = MFMA32(ka, vb[Q][s], S[a]); }
;     }
;     fetch_v(min(step + 2, s1 - 1), PP);
;   };
;   fetch(s0, IC<0>{}, true); fetch(min(s0 + 1, s1 - 1), IC<1>{}, true);
; #pragma unroll 1
;   for (int step = s0; step < s1; step += 2) {
;     body(step, IC<0>{});
;     if (step + 1 < s1) body(step + 1, IC<1>{});
;   }
.LBB0_316:
	s_waitcnt vmcnt(0)
	v_cndmask_b32_e64 v134, v134, v170, s[0:1]
	v_cndmask_b32_e64 v135, v135, v169, s[0:1]
	v_mov_b32_e32 v191, v165
	v_mov_b32_e32 v190, v168
	s_cmp_lt_u32 s31, s30
	s_cbranch_scc0 .LBB0_318
.LBB0_317:
	s_mov_b32 s33, s31
	s_waitcnt vmcnt(6)
	v_mov_b32_e32 v169, v173
	v_mov_b32_e32 v165, v191
	v_mov_b32_e32 v170, v172
	v_mov_b32_e32 v168, v190
	s_branch .LBB0_302
